# slot fusion v6: like v5 but the pass-1 row copy is overlapped with the phase-7 GEMM instead of phase 6 (tables stay in phase 6)
# baseline (speedup 1.0000x reference)
; DEVI char* wsp(const Params& P, size_t off) { asm volatile("" : "+s"(off)); return P.ws + off; }
; DEVI int ltid() { int t = threadIdx.x; asm volatile("" : "+v"(t)); return t; }
; DEVI void phase_xcopy(const Params& P) {
;   const int tid = ltid();
;   bfu* xb = (bfu*)wsp(P, O_XB);
;   for (int it = blockIdx.x; it < 16640; it += gridDim.x) {
;     TokInfo ti = tokinfo(it);
;     const float* src = ti.sample ? P.in[1] + (long)(ti.seq * 32 + ti.t) * 1024 : P.in[0] + (long)(ti.seq * 4096 + ti.t) * 1024;
;     float* dst = xrow(P, it);
;     int c = tid * 4;
;     float4 v = *reinterpret_cast<const float4*>(src + c);
;     *reinterpret_cast<float4*>(dst + c) = v;
;     uint2 r;
;     r.x = f2b(v.x) | ((unsigned)f2b(v.y) << 16);
;     r.y = f2b(v.z) | ((unsigned)f2b(v.w) << 16);
;     *reinterpret_cast<uint2*>(xb + (long)it * 1024 + c) = r;
;   }
; }
; DEVI void phase7(const Params& P, int l, int pass, char* smem) {
;   const int tid = ltid();
;   const int ntok = pass ? 8192 : 8448, base = pass ? 8448 : 0;
;   const int nM = ntok / 128, nN = 8;
;   const bfu* M = (const bfu*)wsp(P, O_CB);
;   const bfu* W = (const bfu*)wsp(P, O_WO);
;   float* pre = (float*)wsp(P, O_PRE);
;   for (int id = blockIdx.x; id < nM * nN; id += gridDim.x) {
;     int pm, pn; tile_rc_m(id, nM, nN, pm, pn);
.LBB0_780:
	s_or_b64 exec, exec, s[26:27]
	s_barrier
	v_readlane_b32 s60, v252, 36
	s_cmp_lg_u32 s60, 0
	s_cbranch_scc1 .Ltb_skip_e
	v_readlane_b32 s60, v252, 32
	s_cmpk_lt_u32 s60, 0x100
	s_cbranch_scc0 .Ltb_skip_e
	s_cmp_lg_u32 s0, 0
	s_cbranch_scc1 .Ltb_skip_e
	v_readlane_b32 s44, v253, 2
	v_readlane_b32 s45, v253, 3
	v_readlane_b32 s60, v252, 32
	s_nop 4
	s_load_dwordx2 s[42:43], s[44:45], 0x0
	v_lshlrev_b32_e32 v248, 4, v93
	v_lshlrev_b32_e32 v250, 3, v93
	v_mov_b32_e32 v251, 0
	v_lshl_add_u64 v[250:251], v[64:65], 0, v[250:251]
	s_waitcnt lgkmcnt(0)

; DEVI char* wsp(const Params& P, size_t off) { asm volatile("" : "+s"(off)); return P.ws + off; }
; DEVI int ltid() { int t = threadIdx.x; asm volatile("" : "+v"(t)); return t; }
; #define ZERO_ACC(a) _Pragma("unroll") for (int m_ = 0; m_ < 4; ++m_) _Pragma("unroll") for (int n_ = 0; n_ < 4; ++n_) a[m_][n_] = f32x4{0.f, 0.f, 0.f, 0.f}
; DEVI void phase7(const Params& P, int l, int pass, char* smem) {
;   const int tid = ltid();
;   const int ntok = pass ? 8192 : 8448, base = pass ? 8448 : 0;
;   const int nM = ntok / 128, nN = 8;
;   const bfu* M = (const bfu*)wsp(P, O_CB);
;   const bfu* W = (const bfu*)wsp(P, O_WO);
;   float* pre = (float*)wsp(P, O_PRE);
;   for (int id = blockIdx.x; id < nM * nN; id += gridDim.x) {
;     int pm, pn; tile_rc_m(id, nM, nN, pm, pn);
;     f32x4 acc[4][4]; ZERO_ACC(acc);
;     gemm_core(acc, M + (long)pm * 128 * 1024, 1024, W + (long)pn * 128 * 1024, 1024, 1024, smem, tid);
.Ltb_skip_e:
	s_cmp_eq_u32 s90, 0
	s_cselect_b64 s[44:45], -1, 0
	s_and_b64 s[26:27], s[44:45], exec
	s_movk_i32 s1, 0x210
	s_cselect_b32 s1, s1, 0x200
	v_mov_b32_e32 v91, v93
	s_mov_b64 s[42:43], 0x17d02000
	s_mov_b64 s[40:41], 0x1e00000
	s_mov_b64 s[26:27], 0x8582000
	s_cmp_ge_i32 s74, s1
	s_cbranch_scc1 .LBB0_855
	v_lshlrev_b32_e32 v146, 4, v91
	v_lshrrev_b32_e32 v5, 4, v91
	v_add_u32_e32 v149, 0x3000, v146
	v_and_b32_e32 v24, 7, v91
	v_ashrrev_i32_e32 v18, 7, v149
	v_bitop3_b32 v5, v5, v24, 3 bitop3:0x6c
	v_bfe_u32 v11, v91, 4, 2
	v_xor_b32_e32 v17, v18, v91
	v_lshlrev_b32_e32 v150, 4, v5
	v_lshlrev_b32_e32 v5, 7, v91
	v_lshlrev_b32_e32 v17, 3, v17
	v_and_b32_e32 v152, 0x2780, v5
	v_bitop3_b32 v5, v11, v24, 4 bitop3:0x36
	v_ashrrev_i32_e32 v0, 3, v91
	v_and_b32_e32 v22, 56, v17
	v_and_b32_e32 v17, 15, v91
	v_lshrrev_b32_e32 v23, 1, v91
	s_mov_b32 s4, 0x1ffffc0
	v_lshlrev_b32_e32 v153, 4, v5
	v_lshrrev_b32_e32 v5, 2, v91
	v_ashrrev_i32_e32 v1, 31, v0
	v_and_or_b32 v17, v23, s4, v17
	v_and_b32_e32 v5, 12, v5
	s_mov_b32 s4, 0x7fffc0
	v_xor_b32_e32 v4, v0, v91
	v_lshlrev_b64 v[2:3], 10, v[0:1]
	v_add_u32_e32 v147, 0x1000, v146
	v_and_or_b32 v5, v23, s4, v5
	v_lshlrev_b64 v[24:25], 11, v[0:1]
	v_bitop3_b32 v0, v0, 7, v91 bitop3:0x48
	v_ashrrev_i32_e32 v6, 7, v147
	v_and_b32_e32 v11, 0x4f, v91
	v_lshlrev_b32_e32 v5, 9, v5
	v_lshl_add_u64 v[26:27], s[42:43], 0, v[24:25]
	v_lshlrev_b32_e32 v88, 4, v0
	v_readlane_b32 s4, v252, 25
	v_ashrrev_i32_e32 v7, 31, v6
	v_lshl_or_b32 v154, v11, 2, v5
	v_lshlrev_b32_e32 v5, 2, v91
	v_lshl_add_u64 v[0:1], v[26:27], 0, v[88:89]
	v_readlane_b32 s5, v252, 26
	v_add_u32_e32 v148, 0x2000, v146
	v_and_b32_e32 v155, 0x7c, v5
	v_lshl_add_u64 v[100:101], s[4:5], 0, v[0:1]
	v_lshlrev_b64 v[0:1], 11, v[6:7]
	v_bitop3_b32 v5, v6, 7, v91 bitop3:0x48
	v_xor_b32_e32 v10, v6, v91
	v_lshlrev_b64 v[8:9], 10, v[6:7]
	v_ashrrev_i32_e32 v12, 7, v148
	v_lshl_add_u64 v[26:27], s[42:43], 0, v[0:1]
	v_lshlrev_b32_e32 v6, 4, v5
	v_mov_b32_e32 v7, v89
	v_ashrrev_i32_e32 v13, 31, v12
	v_lshl_add_u64 v[26:27], v[26:27], 0, v[6:7]
	s_and_b64 s[44:45], s[44:45], exec
	v_lshl_add_u64 v[102:103], s[4:5], 0, v[26:27]
	v_lshlrev_b64 v[26:27], 11, v[12:13]
	v_bitop3_b32 v5, v12, 7, v91 bitop3:0x48
	v_lshl_add_u64 v[0:1], s[40:41], 0, v[0:1]
	s_cselect_b32 s2, 0, 0x2100
	s_add_u32 s24, s30, s42
	v_xor_b32_e32 v16, v12, v91
	v_lshlrev_b64 v[14:15], 10, v[12:13]
	v_lshl_add_u64 v[28:29], s[42:43], 0, v[26:27]
	v_lshlrev_b32_e32 v12, 4, v5
	v_mov_b32_e32 v13, v89
	v_lshl_add_u64 v[0:1], v[0:1], 0, v[6:7]
	s_addc_u32 s46, s31, s43
	v_ashrrev_i32_e32 v19, 31, v18
	v_lshl_add_u64 v[28:29], v[28:29], 0, v[12:13]
	v_lshl_add_u64 v[110:111], s[4:5], 0, v[0:1]
	v_lshl_add_u64 v[0:1], s[40:41], 0, v[26:27]
	s_add_u32 s47, s30, s40
	v_lshl_add_u64 v[104:105], s[4:5], 0, v[28:29]
	v_lshlrev_b64 v[28:29], 11, v[18:19]
	v_bitop3_b32 v5, v18, 7, v91 bitop3:0x48
	v_lshl_add_u64 v[0:1], v[0:1], 0, v[12:13]
	s_addc_u32 s48, s31, s41
	v_lshlrev_b32_e32 v4, 3, v4
	v_lshlrev_b32_e32 v10, 3, v10
	v_lshlrev_b32_e32 v16, 3, v16
	v_lshlrev_b64 v[20:21], 10, v[18:19]
	v_lshl_add_u64 v[30:31], s[42:43], 0, v[28:29]
	v_lshlrev_b32_e32 v18, 4, v5
	v_mov_b32_e32 v19, v89
	v_lshl_add_u64 v[24:25], s[40:41], 0, v[24:25]
	v_lshl_add_u64 v[112:113], s[4:5], 0, v[0:1]
	v_lshl_add_u64 v[0:1], s[40:41], 0, v[28:29]
	s_add_u32 s26, s30, s26
	v_and_b32_e32 v4, 56, v4
	v_and_b32_e32 v10, 56, v10
	v_and_b32_e32 v16, 56, v16
	v_lshl_add_u64 v[30:31], v[30:31], 0, v[18:19]
	v_lshl_add_u64 v[24:25], v[24:25], 0, v[88:89]
	v_lshl_add_u64 v[0:1], v[0:1], 0, v[18:19]
	s_addc_u32 s27, s31, s27
	v_lshlrev_b32_e32 v151, 7, v17
	v_lshlrev_b32_e32 v156, 2, v155
	v_lshl_add_u64 v[106:107], s[4:5], 0, v[30:31]
	v_lshl_add_u64 v[108:109], s[4:5], 0, v[24:25]
	v_lshl_add_u64 v[114:115], s[4:5], 0, v[0:1]
	v_lshlrev_b64 v[116:117], 1, v[2:3]
	v_lshlrev_b32_e32 v88, 1, v4
	v_lshlrev_b64 v[118:119], 1, v[8:9]
	v_lshlrev_b32_e32 v120, 1, v10
	v_lshlrev_b64 v[122:123], 1, v[14:15]
	v_lshlrev_b32_e32 v124, 1, v16
	v_lshlrev_b64 v[126:127], 1, v[20:21]
	v_lshlrev_b32_e32 v128, 1, v22
	s_mov_b32 s49, s74
	s_branch .LBB0_783

; DEVI char* wsp(const Params& P, size_t off) { asm volatile("" : "+s"(off)); return P.ws + off; }
; DEVI int ltid() { int t = threadIdx.x; asm volatile("" : "+v"(t)); return t; }
; #define ZERO_ACC(a) _Pragma("unroll") for (int m_ = 0; m_ < 4; ++m_) _Pragma("unroll") for (int n_ = 0; n_ < 4; ++n_) a[m_][n_] = f32x4{0.f, 0.f, 0.f, 0.f}
; DEVI void phase_xcopy(const Params& P) {
;   const int tid = ltid();
;   bfu* xb = (bfu*)wsp(P, O_XB);
;   for (int it = blockIdx.x; it < 16640; it += gridDim.x) {
;     TokInfo ti = tokinfo(it);
;     const float* src = ti.sample ? P.in[1] + (long)(ti.seq * 32 + ti.t) * 1024 : P.in[0] + (long)(ti.seq * 4096 + ti.t) * 1024;
;     float* dst = xrow(P, it);
;     int c = tid * 4;
;     float4 v = *reinterpret_cast<const float4*>(src + c);
;     *reinterpret_cast<float4*>(dst + c) = v;
;     uint2 r;
;     r.x = f2b(v.x) | ((unsigned)f2b(v.y) << 16);
;     r.y = f2b(v.z) | ((unsigned)f2b(v.w) << 16);
;     *reinterpret_cast<uint2*>(xb + (long)it * 1024 + c) = r;
;   }
; }
; DEVI void phase7(const Params& P, int l, int pass, char* smem) {
;     ...
;   for (int id = blockIdx.x; id < nM * nN; id += gridDim.x) {
;     int pm, pn; tile_rc_m(id, nM, nN, pm, pn);
;     f32x4 acc[4][4]; ZERO_ACC(acc);
;     gemm_core(acc, M + (long)pm * 128 * 1024, 1024, W + (long)pn * 128 * 1024, 1024, 1024, smem, tid);
;     epi_stage_f32(acc, smem, tid);
;     {
;       const float* T = reinterpret_cast<const float*>(smem);
; #pragma unroll 8
;       for (int q = 0; q < 16; ++q) {
;         const int id = tid + 256 * q, row = id >> 5, c4 = id & 31;
;         const int grow = pm * 128 + row, gcol = pn * 128 + c4 * 4;
;         float4 a = *reinterpret_cast<const float4*>(T + row * 128 + c4 * 4);
;         float4 xx = *reinterpret_cast<const float4*>(xrow(P, base + grow) + gcol);
;         *reinterpret_cast<float4*>(pre + (long)grow * 1024 + gcol) =
;             make_float4(ALPHA * xx.x + a.x, ALPHA * xx.y + a.y, ALPHA * xx.z + a.z, ALPHA * xx.w + a.w);
;       }
;     }
;   }
; }
.LBB0_855:
	v_readlane_b32 s60, v252, 36
	s_cmp_lg_u32 s60, 0
	s_cbranch_scc1 .Ltb_skip_f
	v_readlane_b32 s60, v252, 32
	s_cmpk_lt_u32 s60, 0x100
	s_cbranch_scc1 .Ltb_skip_f
	s_cmp_lg_u32 s0, 0
	s_cbranch_scc1 .Ltb_skip_f
	v_readlane_b32 s44, v253, 2
	v_readlane_b32 s45, v253, 3
	v_readlane_b32 s60, v252, 32
	s_nop 4
	s_load_dwordx2 s[42:43], s[44:45], 0x0
	v_lshlrev_b32_e32 v248, 4, v93
	v_lshlrev_b32_e32 v250, 3, v93
	v_mov_b32_e32 v251, 0
	v_lshl_add_u64 v[250:251], v[64:65], 0, v[250:251]
	s_waitcnt lgkmcnt(0)
